# removed 13 compiler-inserted vmcnt(0) before ds_reads in both GEMM K-loops (LDS-DMA now spans phases as designed, vmcnt(6))
# speedup vs baseline: 1.0158x; 1.0158x over previous
.LBB0_379:
	v_lshrrev_b32_e32 v2, 1, v0
	v_and_b32_e32 v2, 24, v2
	s_sext_i32_i8 s80, s0
	s_and_b64 s[36:37], s[8:9], exec
	s_movk_i32 s0, 0x1a40
	v_and_b32_e32 v1, 15, v0
	v_lshlrev_b32_e32 v3, 1, v2
	v_lshlrev_b32_e32 v0, 2, v0
	s_cselect_b32 s59, s0, 0x2040
	v_lshl_or_b32 v136, s4, 6, v1
	v_lshl_or_b32 v1, v1, 6, v3
	s_lshl_b32 s0, s4, 13
	v_and_b32_e32 v0, 32, v0
	v_bitop3_b32 v139, v1, s0, v0 bitop3:0xde
	s_lshl_b32 s0, s1, 5
	s_and_b32 s4, s0, 0x60
	s_lshl_b32 s0, s4, 7
	v_readlane_b32 s7, v253, 40
	v_bitop3_b32 v146, v1, s0, v0 bitop3:0xde
	s_add_u32 s0, s12, s7
	v_mov_b32_e32 v133, v145
	s_addc_u32 s1, s13, 0
	s_add_i32 s62, s45, 0x18000
	v_mov_b32_e32 v129, v145
	v_lshl_add_u64 v[0:1], s[0:1], 0, v[132:133]
	s_mov_b32 m0, s62
	s_add_i32 s63, s45, 0x1a000
	s_waitcnt vmcnt(4)
	s_barrier
	global_load_lds_dwordx4 v[0:1], off
	v_lshl_add_u64 v[0:1], s[0:1], 0, v[128:129]
	s_add_u32 s0, s14, s7
	v_mov_b32_e32 v135, v145
	s_mov_b32 m0, s63
	s_addc_u32 s1, s15, 0
	s_add_i32 s76, s45, 0x8000
	v_mov_b32_e32 v131, v145
	global_load_lds_dwordx4 v[0:1], off
	v_lshl_add_u64 v[0:1], s[0:1], 0, v[134:135]
	s_mov_b32 m0, s76
	s_add_i32 s77, s45, 0xa000
	global_load_lds_dwordx4 v[0:1], off
	v_lshl_add_u64 v[0:1], s[0:1], 0, v[130:131]
	s_add_u32 s0, s5, s7
	s_mov_b32 m0, s77
	s_addc_u32 s1, s6, 0
	s_add_i32 s78, s45, 0x1c000
	global_load_lds_dwordx4 v[0:1], off
	v_lshl_add_u64 v[0:1], s[0:1], 0, v[132:133]
	s_mov_b32 m0, s78
	s_add_i32 s79, s45, 0x1e000
	global_load_lds_dwordx4 v[0:1], off
	v_lshl_add_u64 v[0:1], s[0:1], 0, v[128:129]
	s_mov_b32 m0, s79
	v_ashrrev_i32_e32 v137, 31, v136
	global_load_lds_dwordx4 v[0:1], off
	v_or_b32_e32 v0, 16, v136
	v_ashrrev_i32_e32 v1, 31, v0
	v_lshlrev_b64 v[140:141], 9, v[136:137]
	v_lshlrev_b64 v[142:143], 9, v[0:1]
	v_or_b32_e32 v0, 32, v136
	s_mov_b64 s[0:1], 0x10000
	v_ashrrev_i32_e32 v1, 31, v0
	v_lshl_add_u64 v[152:153], v[140:141], 0, s[0:1]
	s_mov_b64 s[0:1], 0x12000
	s_waitcnt vmcnt(6)
	v_lshlrev_b64 v[148:149], 9, v[0:1]
	v_or_b32_e32 v0, 48, v136
	v_lshl_add_u64 v[154:155], v[140:141], 0, s[0:1]
	s_mov_b64 s[0:1], 0x14000
	v_ashrrev_i32_e32 v1, 31, v0
	v_lshl_add_u64 v[156:157], v[140:141], 0, s[0:1]
	s_mov_b64 s[0:1], 0x16000
	s_mov_b32 s60, 0
	v_or_b32_e32 v138, s4, v2
	v_lshlrev_b64 v[150:151], 9, v[0:1]
	v_lshl_add_u64 v[158:159], v[140:141], 0, s[0:1]
	s_add_i32 s81, s45, 0xc000
	s_add_i32 s82, s45, 0xe000
	s_barrier
	s_branch .LBB0_381

.LBB0_388:
	s_cmpk_eq_i32 s85, 0xf80
	s_cselect_b32 s39, s5, s15
	s_cselect_b32 s38, s4, s14
	s_cselect_b32 s88, s7, s13
	s_cselect_b32 s89, s6, s12
	s_add_i32 s36, s86, 3
	s_cmpk_eq_i32 s85, 0xf80
	s_cselect_b32 s36, 1, s36
	s_add_i32 s87, s86, 2
	s_cmpk_eq_i32 s85, 0xf80
	s_cselect_b32 s37, 0, s87
	v_or_b32_e32 v137, 0x10000, v146
	s_add_i32 s37, s37, s64
	s_add_i32 s36, s36, s64
	v_add_u32_e32 v144, 0x10400, v146
	ds_read_b128 v[160:163], v137
	ds_read_b128 v[164:167], v144
	v_add_u32_e32 v137, 0x10800, v146
	s_add_i32 s40, s66, s85
	s_lshl_b32 s37, s37, 7
	s_lshl_b32 s36, s36, 7
	v_add_u32_e32 v144, 0x10c00, v146
	ds_read_b128 v[168:171], v137
	ds_read_b128 v[188:191], v144
	s_and_b32 s91, s40, 0xf80
	s_and_b32 s92, s37, 0xf80
	s_and_b32 s90, s36, 0xf80
	s_add_u32 s36, s38, s90
	s_addc_u32 s37, s39, 0
	s_add_u32 s40, s89, s92
	s_addc_u32 s41, s88, 0
	s_add_u32 s91, s14, s91
	s_addc_u32 s93, s15, 0
	s_add_u32 s38, s38, s92
	s_addc_u32 s39, s39, 0
	s_add_u32 s92, s91, 0x84000
	s_addc_u32 s93, s93, 0
	s_mov_b32 m0, s81
	v_lshl_add_u64 v[172:173], s[92:93], 0, v[134:135]
	ds_read_b128 v[192:195], v139
	ds_read_b128 v[196:199], v139 offset:1024
	ds_read_b128 v[200:203], v139 offset:2048
	ds_read_b128 v[204:207], v139 offset:3072
	ds_read_b128 v[208:211], v139 offset:4096
	ds_read_b128 v[212:215], v139 offset:5120
	ds_read_b128 v[216:219], v139 offset:6144
	ds_read_b128 v[220:223], v139 offset:7168
	global_load_lds_dwordx4 v[172:173], off
	v_lshl_add_u64 v[172:173], s[92:93], 0, v[130:131]
	s_mov_b32 m0, s82
	s_nop 0
	global_load_lds_dwordx4 v[172:173], off
	s_waitcnt lgkmcnt(8)
	s_barrier
	s_waitcnt lgkmcnt(0)
	s_setprio 1
	s_waitcnt lgkmcnt(0)
	v_mfma_f32_16x16x32_bf16 v[124:127], v[160:163], v[192:195], v[124:127]
	v_mfma_f32_16x16x32_bf16 v[120:123], v[168:171], v[192:195], v[120:123]
	v_mfma_f32_16x16x32_bf16 v[112:115], v[160:163], v[200:203], v[112:115]
	v_mfma_f32_16x16x32_bf16 v[108:111], v[168:171], v[200:203], v[108:111]
	v_mfma_f32_16x16x32_bf16 v[104:107], v[160:163], v[208:211], v[104:107]
	v_mfma_f32_16x16x32_bf16 v[96:99], v[168:171], v[208:211], v[96:99]
	v_mfma_f32_16x16x32_bf16 v[88:91], v[160:163], v[216:219], v[88:91]
	v_mfma_f32_16x16x32_bf16 v[80:83], v[168:171], v[216:219], v[80:83]
	v_mfma_f32_16x16x32_bf16 v[124:127], v[164:167], v[196:199], v[124:127]
	v_mfma_f32_16x16x32_bf16 v[120:123], v[188:191], v[196:199], v[120:123]
	v_mfma_f32_16x16x32_bf16 v[112:115], v[164:167], v[204:207], v[112:115]
	v_mfma_f32_16x16x32_bf16 v[108:111], v[188:191], v[204:207], v[108:111]
	v_mfma_f32_16x16x32_bf16 v[104:107], v[164:167], v[212:215], v[104:107]
	v_mfma_f32_16x16x32_bf16 v[96:99], v[188:191], v[212:215], v[96:99]
	v_mfma_f32_16x16x32_bf16 v[88:91], v[164:167], v[220:223], v[88:91]
	v_mfma_f32_16x16x32_bf16 v[80:83], v[188:191], v[220:223], v[80:83]
	s_setprio 0
	s_barrier
	v_or_b32_e32 v137, 0x14000, v146
	s_mov_b32 m0, s52
	v_add_u32_e32 v144, 0x14400, v146
	ds_read_b128 v[224:227], v137
	ds_read_b128 v[228:231], v144
	v_add_u32_e32 v137, 0x14800, v146
	v_lshl_add_u64 v[172:173], s[40:41], 0, v[132:133]
	v_add_u32_e32 v144, 0x14c00, v146
	ds_read_b128 v[232:235], v137
	ds_read_b128 v[236:239], v144
	global_load_lds_dwordx4 v[172:173], off
	v_lshl_add_u64 v[172:173], s[40:41], 0, v[128:129]
	s_mov_b32 m0, s53
	s_nop 0
	global_load_lds_dwordx4 v[172:173], off
	s_barrier
	s_waitcnt lgkmcnt(0)
	s_setprio 1
	s_waitcnt lgkmcnt(0)
	v_mfma_f32_16x16x32_bf16 v[116:119], v[224:227], v[192:195], v[116:119]
	v_mfma_f32_16x16x32_bf16 v[100:103], v[232:235], v[192:195], v[100:103]
	v_mfma_f32_16x16x32_bf16 v[92:95], v[224:227], v[200:203], v[92:95]
	v_mfma_f32_16x16x32_bf16 v[84:87], v[232:235], v[200:203], v[84:87]
	v_mfma_f32_16x16x32_bf16 v[76:79], v[224:227], v[208:211], v[76:79]
	v_mfma_f32_16x16x32_bf16 v[72:75], v[232:235], v[208:211], v[72:75]
	v_mfma_f32_16x16x32_bf16 v[68:71], v[224:227], v[216:219], v[68:71]
	v_mfma_f32_16x16x32_bf16 v[64:67], v[232:235], v[216:219], v[64:67]
	v_mfma_f32_16x16x32_bf16 v[116:119], v[228:231], v[196:199], v[116:119]
	v_mfma_f32_16x16x32_bf16 v[100:103], v[236:239], v[196:199], v[100:103]
	v_mfma_f32_16x16x32_bf16 v[92:95], v[228:231], v[204:207], v[92:95]
	v_mfma_f32_16x16x32_bf16 v[84:87], v[236:239], v[204:207], v[84:87]
	v_mfma_f32_16x16x32_bf16 v[76:79], v[228:231], v[212:215], v[76:79]
	v_mfma_f32_16x16x32_bf16 v[72:75], v[236:239], v[212:215], v[72:75]
	v_mfma_f32_16x16x32_bf16 v[68:71], v[228:231], v[220:223], v[68:71]
	v_mfma_f32_16x16x32_bf16 v[64:67], v[236:239], v[220:223], v[64:67]
	s_setprio 0
	s_mov_b32 m0, s45
	v_lshl_add_u64 v[172:173], s[38:39], 0, v[134:135]
	s_barrier
	ds_read_b128 v[192:195], v139 offset:16384
	ds_read_b128 v[196:199], v139 offset:17408
	ds_read_b128 v[200:203], v139 offset:18432
	ds_read_b128 v[204:207], v139 offset:19456
	ds_read_b128 v[208:211], v139 offset:20480
	ds_read_b128 v[212:215], v139 offset:21504
	ds_read_b128 v[216:219], v139 offset:22528
	ds_read_b128 v[220:223], v139 offset:23552
	global_load_lds_dwordx4 v[172:173], off
	v_lshl_add_u64 v[172:173], s[38:39], 0, v[130:131]
	s_mov_b32 m0, s54
	s_nop 0
	global_load_lds_dwordx4 v[172:173], off
	s_barrier
	s_waitcnt lgkmcnt(0)
	s_setprio 1
	s_waitcnt lgkmcnt(0)
	v_mfma_f32_16x16x32_bf16 v[60:63], v[160:163], v[192:195], v[60:63]
	v_mfma_f32_16x16x32_bf16 v[56:59], v[168:171], v[192:195], v[56:59]
	v_mfma_f32_16x16x32_bf16 v[52:55], v[160:163], v[200:203], v[52:55]
	v_mfma_f32_16x16x32_bf16 v[48:51], v[168:171], v[200:203], v[48:51]
	v_mfma_f32_16x16x32_bf16 v[40:43], v[160:163], v[208:211], v[40:43]
	v_mfma_f32_16x16x32_bf16 v[36:39], v[168:171], v[208:211], v[36:39]
	v_mfma_f32_16x16x32_bf16 v[24:27], v[160:163], v[216:219], v[24:27]
	v_mfma_f32_16x16x32_bf16 v[20:23], v[168:171], v[216:219], v[20:23]
	v_mfma_f32_16x16x32_bf16 v[60:63], v[164:167], v[196:199], v[60:63]
	v_mfma_f32_16x16x32_bf16 v[56:59], v[188:191], v[196:199], v[56:59]
	v_mfma_f32_16x16x32_bf16 v[52:55], v[164:167], v[204:207], v[52:55]
	v_mfma_f32_16x16x32_bf16 v[48:51], v[188:191], v[204:207], v[48:51]
	v_mfma_f32_16x16x32_bf16 v[40:43], v[164:167], v[212:215], v[40:43]
	v_mfma_f32_16x16x32_bf16 v[36:39], v[188:191], v[212:215], v[36:39]
	v_mfma_f32_16x16x32_bf16 v[24:27], v[164:167], v[220:223], v[24:27]
	v_mfma_f32_16x16x32_bf16 v[20:23], v[188:191], v[220:223], v[20:23]
	s_setprio 0
	s_barrier
	s_add_u32 s40, s40, 0x84000
	s_addc_u32 s41, s41, 0
	s_mov_b32 m0, s55
	v_lshl_add_u64 v[160:161], s[40:41], 0, v[132:133]
	global_load_lds_dwordx4 v[160:161], off
	v_lshl_add_u64 v[160:161], s[40:41], 0, v[128:129]
	s_mov_b32 m0, s56
	s_nop 0
	global_load_lds_dwordx4 v[160:161], off
	s_waitcnt vmcnt(6)
	s_barrier
	s_setprio 1
	v_mfma_f32_16x16x32_bf16 v[44:47], v[224:227], v[192:195], v[44:47]
	v_mfma_f32_16x16x32_bf16 v[32:35], v[232:235], v[192:195], v[32:35]
	v_mfma_f32_16x16x32_bf16 v[28:31], v[224:227], v[200:203], v[28:31]
	v_mfma_f32_16x16x32_bf16 v[16:19], v[232:235], v[200:203], v[16:19]
	v_mfma_f32_16x16x32_bf16 v[12:15], v[224:227], v[208:211], v[12:15]
	v_mfma_f32_16x16x32_bf16 v[8:11], v[232:235], v[208:211], v[8:11]
	v_mfma_f32_16x16x32_bf16 v[4:7], v[224:227], v[216:219], v[4:7]
	v_mfma_f32_16x16x32_bf16 v[0:3], v[232:235], v[216:219], v[0:3]
	v_mfma_f32_16x16x32_bf16 v[44:47], v[228:231], v[196:199], v[44:47]
	v_mfma_f32_16x16x32_bf16 v[32:35], v[236:239], v[196:199], v[32:35]
	v_mfma_f32_16x16x32_bf16 v[28:31], v[228:231], v[204:207], v[28:31]
	v_mfma_f32_16x16x32_bf16 v[16:19], v[236:239], v[204:207], v[16:19]
	v_mfma_f32_16x16x32_bf16 v[12:15], v[228:231], v[212:215], v[12:15]
	v_mfma_f32_16x16x32_bf16 v[8:11], v[236:239], v[212:215], v[8:11]
	v_mfma_f32_16x16x32_bf16 v[4:7], v[228:231], v[220:223], v[4:7]
	v_mfma_f32_16x16x32_bf16 v[0:3], v[236:239], v[220:223], v[0:3]
	s_setprio 0
	v_or_b32_e32 v137, 0x18000, v146
	s_barrier
	v_add_u32_e32 v144, 0x18400, v146
	ds_read_b128 v[160:163], v137
	ds_read_b128 v[164:167], v144
	v_add_u32_e32 v137, 0x18800, v146
	v_add_u32_e32 v144, 0x18c00, v146
	ds_read_b128 v[168:171], v137
	ds_read_b128 v[188:191], v144
	s_add_u32 s38, s38, 0x84000
	s_addc_u32 s39, s39, 0
	s_mov_b32 m0, s57
	v_lshl_add_u64 v[172:173], s[38:39], 0, v[134:135]
	ds_read_b128 v[192:195], v139 offset:32768
	ds_read_b128 v[196:199], v139 offset:33792
	ds_read_b128 v[200:203], v139 offset:34816
	ds_read_b128 v[204:207], v139 offset:35840
	ds_read_b128 v[208:211], v139 offset:36864
	ds_read_b128 v[212:215], v139 offset:37888
	ds_read_b128 v[216:219], v139 offset:38912
	ds_read_b128 v[220:223], v139 offset:39936
	global_load_lds_dwordx4 v[172:173], off
	v_lshl_add_u64 v[172:173], s[38:39], 0, v[130:131]
	s_mov_b32 m0, s58
	s_nop 0
	global_load_lds_dwordx4 v[172:173], off
	s_waitcnt lgkmcnt(8)
	s_barrier
	s_waitcnt lgkmcnt(0)
	s_setprio 1
	s_waitcnt lgkmcnt(0)
	v_mfma_f32_16x16x32_bf16 v[124:127], v[160:163], v[192:195], v[124:127]
	v_mfma_f32_16x16x32_bf16 v[120:123], v[168:171], v[192:195], v[120:123]
	v_mfma_f32_16x16x32_bf16 v[112:115], v[160:163], v[200:203], v[112:115]
	v_mfma_f32_16x16x32_bf16 v[108:111], v[168:171], v[200:203], v[108:111]
	v_mfma_f32_16x16x32_bf16 v[104:107], v[160:163], v[208:211], v[104:107]
	v_mfma_f32_16x16x32_bf16 v[96:99], v[168:171], v[208:211], v[96:99]
	v_mfma_f32_16x16x32_bf16 v[88:91], v[160:163], v[216:219], v[88:91]
	v_mfma_f32_16x16x32_bf16 v[80:83], v[168:171], v[216:219], v[80:83]
	v_mfma_f32_16x16x32_bf16 v[124:127], v[164:167], v[196:199], v[124:127]
	v_mfma_f32_16x16x32_bf16 v[120:123], v[188:191], v[196:199], v[120:123]
	v_mfma_f32_16x16x32_bf16 v[112:115], v[164:167], v[204:207], v[112:115]
	v_mfma_f32_16x16x32_bf16 v[108:111], v[188:191], v[204:207], v[108:111]
	v_mfma_f32_16x16x32_bf16 v[104:107], v[164:167], v[212:215], v[104:107]
	v_mfma_f32_16x16x32_bf16 v[96:99], v[188:191], v[212:215], v[96:99]
	v_mfma_f32_16x16x32_bf16 v[88:91], v[164:167], v[220:223], v[88:91]
	v_mfma_f32_16x16x32_bf16 v[80:83], v[188:191], v[220:223], v[80:83]
	s_setprio 0
	s_barrier
	s_add_u32 s38, s89, s90
	v_or_b32_e32 v137, 0x1c000, v146
	s_addc_u32 s39, s88, 0
	s_mov_b32 m0, s62
	v_add_u32_e32 v144, 0x1c400, v146
	ds_read_b128 v[224:227], v137
	ds_read_b128 v[228:231], v144
	v_add_u32_e32 v137, 0x1c800, v146
	v_lshl_add_u64 v[172:173], s[38:39], 0, v[132:133]
	v_add_u32_e32 v144, 0x1cc00, v146
	ds_read_b128 v[232:235], v137
	ds_read_b128 v[236:239], v144
	global_load_lds_dwordx4 v[172:173], off
	v_lshl_add_u64 v[172:173], s[38:39], 0, v[128:129]
	s_mov_b32 m0, s63
	s_nop 0
	global_load_lds_dwordx4 v[172:173], off
	s_barrier
	s_waitcnt lgkmcnt(0)
	s_setprio 1
	s_waitcnt lgkmcnt(0)
	v_mfma_f32_16x16x32_bf16 v[116:119], v[224:227], v[192:195], v[116:119]
	v_mfma_f32_16x16x32_bf16 v[100:103], v[232:235], v[192:195], v[100:103]
	v_mfma_f32_16x16x32_bf16 v[92:95], v[224:227], v[200:203], v[92:95]
	v_mfma_f32_16x16x32_bf16 v[84:87], v[232:235], v[200:203], v[84:87]
	v_mfma_f32_16x16x32_bf16 v[76:79], v[224:227], v[208:211], v[76:79]
	v_mfma_f32_16x16x32_bf16 v[72:75], v[232:235], v[208:211], v[72:75]
	v_mfma_f32_16x16x32_bf16 v[68:71], v[224:227], v[216:219], v[68:71]
	v_mfma_f32_16x16x32_bf16 v[64:67], v[232:235], v[216:219], v[64:67]
	v_mfma_f32_16x16x32_bf16 v[116:119], v[228:231], v[196:199], v[116:119]
	v_mfma_f32_16x16x32_bf16 v[100:103], v[236:239], v[196:199], v[100:103]
	v_mfma_f32_16x16x32_bf16 v[92:95], v[228:231], v[204:207], v[92:95]
	v_mfma_f32_16x16x32_bf16 v[84:87], v[236:239], v[204:207], v[84:87]
	v_mfma_f32_16x16x32_bf16 v[76:79], v[228:231], v[212:215], v[76:79]
	v_mfma_f32_16x16x32_bf16 v[72:75], v[236:239], v[212:215], v[72:75]
	v_mfma_f32_16x16x32_bf16 v[68:71], v[228:231], v[220:223], v[68:71]
	v_mfma_f32_16x16x32_bf16 v[64:67], v[236:239], v[220:223], v[64:67]
	s_setprio 0
	s_mov_b32 m0, s76
	v_lshl_add_u64 v[172:173], s[36:37], 0, v[134:135]
	s_barrier
	ds_read_b128 v[192:195], v139 offset:49152
	ds_read_b128 v[196:199], v139 offset:50176
	ds_read_b128 v[200:203], v139 offset:51200
	ds_read_b128 v[204:207], v139 offset:52224
	ds_read_b128 v[208:211], v139 offset:53248
	ds_read_b128 v[212:215], v139 offset:54272
	ds_read_b128 v[216:219], v139 offset:55296
	ds_read_b128 v[220:223], v139 offset:56320
	global_load_lds_dwordx4 v[172:173], off
	v_lshl_add_u64 v[172:173], s[36:37], 0, v[130:131]
	s_mov_b32 m0, s77
	s_nop 0
	global_load_lds_dwordx4 v[172:173], off
	s_barrier
	s_waitcnt lgkmcnt(0)
	s_setprio 1
	s_waitcnt lgkmcnt(0)
	v_mfma_f32_16x16x32_bf16 v[60:63], v[160:163], v[192:195], v[60:63]
	v_mfma_f32_16x16x32_bf16 v[56:59], v[168:171], v[192:195], v[56:59]
	v_mfma_f32_16x16x32_bf16 v[52:55], v[160:163], v[200:203], v[52:55]
	v_mfma_f32_16x16x32_bf16 v[48:51], v[168:171], v[200:203], v[48:51]
	v_mfma_f32_16x16x32_bf16 v[40:43], v[160:163], v[208:211], v[40:43]
	v_mfma_f32_16x16x32_bf16 v[36:39], v[168:171], v[208:211], v[36:39]
	v_mfma_f32_16x16x32_bf16 v[24:27], v[160:163], v[216:219], v[24:27]
	v_mfma_f32_16x16x32_bf16 v[20:23], v[168:171], v[216:219], v[20:23]
	v_mfma_f32_16x16x32_bf16 v[60:63], v[164:167], v[196:199], v[60:63]
	v_mfma_f32_16x16x32_bf16 v[56:59], v[188:191], v[196:199], v[56:59]
	v_mfma_f32_16x16x32_bf16 v[52:55], v[164:167], v[204:207], v[52:55]
	v_mfma_f32_16x16x32_bf16 v[48:51], v[188:191], v[204:207], v[48:51]
	v_mfma_f32_16x16x32_bf16 v[40:43], v[164:167], v[212:215], v[40:43]
	v_mfma_f32_16x16x32_bf16 v[36:39], v[188:191], v[212:215], v[36:39]
	v_mfma_f32_16x16x32_bf16 v[24:27], v[164:167], v[220:223], v[24:27]
	v_mfma_f32_16x16x32_bf16 v[20:23], v[188:191], v[220:223], v[20:23]
	s_setprio 0
	s_barrier
	s_add_u32 s36, s38, 0x84000
	s_addc_u32 s37, s39, 0
	s_mov_b32 m0, s78
	v_lshl_add_u64 v[160:161], s[36:37], 0, v[132:133]
	global_load_lds_dwordx4 v[160:161], off
	v_lshl_add_u64 v[160:161], s[36:37], 0, v[128:129]
	s_mov_b32 m0, s79
	s_nop 0
	global_load_lds_dwordx4 v[160:161], off
	s_waitcnt vmcnt(6)
	s_barrier
	s_setprio 1
	v_mfma_f32_16x16x32_bf16 v[44:47], v[224:227], v[192:195], v[44:47]
	v_mfma_f32_16x16x32_bf16 v[32:35], v[232:235], v[192:195], v[32:35]
	v_mfma_f32_16x16x32_bf16 v[28:31], v[224:227], v[200:203], v[28:31]
	v_mfma_f32_16x16x32_bf16 v[16:19], v[232:235], v[200:203], v[16:19]
	v_mfma_f32_16x16x32_bf16 v[12:15], v[224:227], v[208:211], v[12:15]
	v_mfma_f32_16x16x32_bf16 v[8:11], v[232:235], v[208:211], v[8:11]
	v_mfma_f32_16x16x32_bf16 v[4:7], v[224:227], v[216:219], v[4:7]
	v_mfma_f32_16x16x32_bf16 v[0:3], v[232:235], v[216:219], v[0:3]
	v_mfma_f32_16x16x32_bf16 v[44:47], v[228:231], v[196:199], v[44:47]
	v_mfma_f32_16x16x32_bf16 v[32:35], v[236:239], v[196:199], v[32:35]
	v_mfma_f32_16x16x32_bf16 v[28:31], v[228:231], v[204:207], v[28:31]
	v_mfma_f32_16x16x32_bf16 v[16:19], v[236:239], v[204:207], v[16:19]
	v_mfma_f32_16x16x32_bf16 v[12:15], v[228:231], v[212:215], v[12:15]
	v_mfma_f32_16x16x32_bf16 v[8:11], v[236:239], v[212:215], v[8:11]
	v_mfma_f32_16x16x32_bf16 v[4:7], v[228:231], v[220:223], v[4:7]
	v_mfma_f32_16x16x32_bf16 v[0:3], v[236:239], v[220:223], v[0:3]
	s_setprio 0
	s_addk_i32 s85, 0x100
	s_cmp_gt_u32 s86, 29
	s_mov_b32 s86, s87
	s_barrier
	s_cbranch_scc0 .LBB0_388
	s_lshl_b32 s36, s80, 8
	v_lshl_add_u32 v137, s61, 8, v136
	v_or_b32_e32 v160, s36, v138
	v_ashrrev_i32_e32 v161, 31, v160
	v_mad_i64_i32 v[162:163], s[12:13], s59, v137, 0
	v_lshl_add_u64 v[164:165], v[162:163], 1, s[42:43]
	v_lshlrev_b64 v[162:163], 1, v[160:161]
	v_lshl_add_u64 v[168:169], v[164:165], 0, v[162:163]
	v_cvt_pk_bf16_f32 v164, v124, v125
	v_cvt_pk_bf16_f32 v165, v126, v127
	v_cvt_pk_bf16_f32 v166, v120, v121
	v_cvt_pk_bf16_f32 v167, v122, v123
	global_store_dwordx4 v[168:169], v[164:167], off
	v_or_b32_e32 v144, 16, v137
	s_cmp_lt_i32 s61, 16
	v_cvt_pk_bf16_f32 v164, v116, v117
	v_cvt_pk_bf16_f32 v165, v118, v119
	v_cvt_pk_bf16_f32 v166, v100, v101
	v_cvt_pk_bf16_f32 v167, v102, v103
	global_store_dwordx4 v[168:169], v[164:167], off offset:256
	s_nop 1
	v_mad_i64_i32 v[164:165], s[12:13], s59, v144, 0
	v_lshl_add_u64 v[164:165], v[164:165], 1, s[42:43]
	v_lshl_add_u64 v[168:169], v[164:165], 0, v[162:163]
	v_cvt_pk_bf16_f32 v164, v112, v113
	v_cvt_pk_bf16_f32 v165, v114, v115
	v_cvt_pk_bf16_f32 v166, v108, v109
	v_cvt_pk_bf16_f32 v167, v110, v111
	global_store_dwordx4 v[168:169], v[164:167], off
	v_or_b32_e32 v144, 32, v137
	s_nop 0
	v_cvt_pk_bf16_f32 v164, v92, v93
	v_cvt_pk_bf16_f32 v165, v94, v95
	v_cvt_pk_bf16_f32 v166, v84, v85
	v_cvt_pk_bf16_f32 v167, v86, v87
	global_store_dwordx4 v[168:169], v[164:167], off offset:256
	s_nop 1
	v_mad_i64_i32 v[164:165], s[12:13], s59, v144, 0
	v_lshl_add_u64 v[164:165], v[164:165], 1, s[42:43]
	v_lshl_add_u64 v[168:169], v[164:165], 0, v[162:163]
	v_cvt_pk_bf16_f32 v164, v104, v105
	v_cvt_pk_bf16_f32 v165, v106, v107
	v_cvt_pk_bf16_f32 v166, v96, v97
	v_cvt_pk_bf16_f32 v167, v98, v99
	global_store_dwordx4 v[168:169], v[164:167], off
	v_or_b32_e32 v144, 48, v137
	s_nop 0
	v_cvt_pk_bf16_f32 v164, v76, v77
	v_cvt_pk_bf16_f32 v165, v78, v79
	v_cvt_pk_bf16_f32 v166, v72, v73
	v_cvt_pk_bf16_f32 v167, v74, v75
	global_store_dwordx4 v[168:169], v[164:167], off offset:256
	s_nop 1
	v_mad_i64_i32 v[164:165], s[12:13], s59, v144, 0
	v_lshl_add_u64 v[164:165], v[164:165], 1, s[42:43]
	v_lshl_add_u64 v[168:169], v[164:165], 0, v[162:163]
	v_cvt_pk_bf16_f32 v164, v88, v89
	v_cvt_pk_bf16_f32 v165, v90, v91
	v_cvt_pk_bf16_f32 v166, v80, v81
	v_cvt_pk_bf16_f32 v167, v82, v83
	global_store_dwordx4 v[168:169], v[164:167], off
	v_add_u32_e32 v144, 0x80, v137
	s_nop 0
	v_cvt_pk_bf16_f32 v164, v68, v69
	v_cvt_pk_bf16_f32 v165, v70, v71
	v_cvt_pk_bf16_f32 v166, v64, v65
	v_cvt_pk_bf16_f32 v167, v66, v67
	global_store_dwordx4 v[168:169], v[164:167], off offset:256
	s_nop 1
	v_mad_i64_i32 v[164:165], s[12:13], s59, v144, 0
	v_lshl_add_u64 v[164:165], v[164:165], 1, s[42:43]
	v_lshl_add_u64 v[168:169], v[164:165], 0, v[162:163]
	v_cvt_pk_bf16_f32 v164, v60, v61
	v_cvt_pk_bf16_f32 v165, v62, v63
	v_cvt_pk_bf16_f32 v166, v56, v57
	v_cvt_pk_bf16_f32 v167, v58, v59
	global_store_dwordx4 v[168:169], v[164:167], off
	v_add_u32_e32 v144, 0x90, v137
	s_nop 0
	v_cvt_pk_bf16_f32 v164, v44, v45
	v_cvt_pk_bf16_f32 v165, v46, v47
	v_cvt_pk_bf16_f32 v166, v32, v33
	v_cvt_pk_bf16_f32 v167, v34, v35
	global_store_dwordx4 v[168:169], v[164:167], off offset:256
	s_nop 1
	v_mad_i64_i32 v[164:165], s[12:13], s59, v144, 0
	v_lshl_add_u64 v[164:165], v[164:165], 1, s[42:43]
	v_lshl_add_u64 v[168:169], v[164:165], 0, v[162:163]
	v_cvt_pk_bf16_f32 v164, v52, v53
	v_cvt_pk_bf16_f32 v165, v54, v55
	v_cvt_pk_bf16_f32 v166, v48, v49
	v_cvt_pk_bf16_f32 v167, v50, v51
	global_store_dwordx4 v[168:169], v[164:167], off
	v_add_u32_e32 v144, 0xa0, v137
	v_add_u32_e32 v137, 0xb0, v137
	v_cvt_pk_bf16_f32 v164, v28, v29
	v_cvt_pk_bf16_f32 v165, v30, v31
	v_cvt_pk_bf16_f32 v166, v16, v17
	v_cvt_pk_bf16_f32 v167, v18, v19
	global_store_dwordx4 v[168:169], v[164:167], off offset:256
	s_nop 1
	v_mad_i64_i32 v[164:165], s[12:13], s59, v144, 0
	v_lshl_add_u64 v[164:165], v[164:165], 1, s[42:43]
	v_lshl_add_u64 v[168:169], v[164:165], 0, v[162:163]
	v_cvt_pk_bf16_f32 v164, v40, v41
	v_cvt_pk_bf16_f32 v165, v42, v43
	v_cvt_pk_bf16_f32 v166, v36, v37
	v_cvt_pk_bf16_f32 v167, v38, v39
	global_store_dwordx4 v[168:169], v[164:167], off
	s_nop 1
	v_cvt_pk_bf16_f32 v164, v12, v13
	v_cvt_pk_bf16_f32 v165, v14, v15
	v_cvt_pk_bf16_f32 v166, v8, v9
	v_cvt_pk_bf16_f32 v167, v10, v11
	global_store_dwordx4 v[168:169], v[164:167], off offset:256
	s_nop 1
	v_mad_i64_i32 v[164:165], s[12:13], s59, v137, 0
	s_cselect_b64 s[12:13], -1, 0
	v_lshl_add_u64 v[164:165], v[164:165], 1, s[42:43]
	s_and_b64 s[12:13], s[8:9], s[12:13]
	v_lshl_add_u64 v[166:167], v[164:165], 0, v[162:163]
	v_cvt_pk_bf16_f32 v162, v24, v25
	v_cvt_pk_bf16_f32 v163, v26, v27
	v_cvt_pk_bf16_f32 v164, v20, v21
	v_cvt_pk_bf16_f32 v165, v22, v23
	s_andn2_b64 vcc, exec, s[12:13]
	global_store_dwordx4 v[166:167], v[162:165], off
	s_nop 1
	v_cvt_pk_bf16_f32 v162, v4, v5
	v_cvt_pk_bf16_f32 v163, v6, v7
	v_cvt_pk_bf16_f32 v164, v0, v1
	v_cvt_pk_bf16_f32 v165, v2, v3
	global_store_dwordx4 v[166:167], v[162:165], off offset:256
	s_cbranch_vccnz .LBB0_380
	s_cmp_lt_i32 s80, 5
	s_cbranch_scc1 .LBB0_394
	s_cmp_eq_u32 s80, 5
	s_mov_b64 s[14:15], -1
	s_cbranch_scc0 .LBB0_393
	s_mov_b64 s[14:15], 0

.LBB0_494:
	s_cmpk_eq_i32 s85, 0xf80
	s_cselect_b32 s37, s5, s13
	s_cselect_b32 s36, s4, s12
	s_cselect_b32 s88, s7, s11
	s_cselect_b32 s89, s6, s10
	s_add_i32 s14, s86, 3
	s_cmpk_eq_i32 s85, 0xf80
	s_cselect_b32 s14, 1, s14
	s_add_i32 s87, s86, 2
	s_cmpk_eq_i32 s85, 0xf80
	s_cselect_b32 s15, 0, s87
	v_or_b32_e32 v134, 0x10000, v140
	v_add_u32_e32 v142, 0x10400, v140
	s_add_i32 s15, s15, s64
	s_add_i32 s14, s14, s64
	ds_read_b128 v[134:137], v134
	ds_read_b128 v[148:151], v142
	v_add_u32_e32 v142, 0x10800, v140
	s_add_i32 s38, s66, s85
	s_lshl_b32 s15, s15, 7
	s_lshl_b32 s14, s14, 7
	v_add_u32_e32 v143, 0x10c00, v140
	ds_read_b128 v[152:155], v142
	ds_read_b128 v[156:159], v143
	s_and_b32 s91, s38, 0xf80
	s_and_b32 s92, s15, 0xf80
	s_and_b32 s90, s14, 0xf80
	s_add_u32 s14, s36, s90
	s_addc_u32 s15, s37, 0
	s_add_u32 s38, s89, s92
	s_addc_u32 s39, s88, 0
	s_add_u32 s91, s12, s91
	s_addc_u32 s93, s13, 0
	s_add_u32 s36, s36, s92
	s_addc_u32 s37, s37, 0
	s_add_u32 s92, s91, 0x84000
	s_addc_u32 s93, s93, 0
	v_lshl_add_u64 v[142:143], s[92:93], 0, v[132:133]
	s_add_i32 m0, s41, 0xc000
	ds_read_b128 v[160:163], v139
	ds_read_b128 v[164:167], v139 offset:1024
	ds_read_b128 v[168:171], v139 offset:2048
	ds_read_b128 v[172:175], v139 offset:3072
	ds_read_b128 v[188:191], v139 offset:4096
	ds_read_b128 v[192:195], v139 offset:5120
	ds_read_b128 v[196:199], v139 offset:6144
	ds_read_b128 v[200:203], v139 offset:7168
	global_load_lds_dwordx4 v[142:143], off
	v_lshl_add_u64 v[142:143], s[92:93], 0, v[130:131]
	s_add_i32 m0, s41, 0xe000
	s_nop 0
	global_load_lds_dwordx4 v[142:143], off
	s_waitcnt lgkmcnt(8)
	s_barrier
	s_waitcnt lgkmcnt(0)
	s_setprio 1
	s_waitcnt lgkmcnt(0)
	v_mfma_f32_16x16x32_bf16 v[124:127], v[134:137], v[160:163], v[124:127]
	v_mfma_f32_16x16x32_bf16 v[120:123], v[152:155], v[160:163], v[120:123]
	v_mfma_f32_16x16x32_bf16 v[116:119], v[134:137], v[168:171], v[116:119]
	v_mfma_f32_16x16x32_bf16 v[108:111], v[152:155], v[168:171], v[108:111]
	v_mfma_f32_16x16x32_bf16 v[100:103], v[134:137], v[188:191], v[100:103]
	v_mfma_f32_16x16x32_bf16 v[92:95], v[152:155], v[188:191], v[92:95]
	v_mfma_f32_16x16x32_bf16 v[84:87], v[134:137], v[196:199], v[84:87]
	v_mfma_f32_16x16x32_bf16 v[76:79], v[152:155], v[196:199], v[76:79]
	v_mfma_f32_16x16x32_bf16 v[124:127], v[148:151], v[164:167], v[124:127]
	v_mfma_f32_16x16x32_bf16 v[120:123], v[156:159], v[164:167], v[120:123]
	v_mfma_f32_16x16x32_bf16 v[116:119], v[148:151], v[172:175], v[116:119]
	v_mfma_f32_16x16x32_bf16 v[108:111], v[156:159], v[172:175], v[108:111]
	v_mfma_f32_16x16x32_bf16 v[100:103], v[148:151], v[192:195], v[100:103]
	v_mfma_f32_16x16x32_bf16 v[92:95], v[156:159], v[192:195], v[92:95]
	v_mfma_f32_16x16x32_bf16 v[84:87], v[148:151], v[200:203], v[84:87]
	v_mfma_f32_16x16x32_bf16 v[76:79], v[156:159], v[200:203], v[76:79]
	s_setprio 0
	s_barrier
	v_or_b32_e32 v142, 0x14000, v140
	v_add_u32_e32 v143, 0x14400, v140
	ds_read_b128 v[204:207], v142
	ds_read_b128 v[208:211], v143
	v_add_u32_e32 v142, 0x14800, v140
	v_add_u32_e32 v143, 0x14c00, v140
	s_mov_b32 m0, s44
	ds_read_b128 v[212:215], v142
	ds_read_b128 v[216:219], v143
	v_lshl_add_u64 v[142:143], s[38:39], 0, v[144:145]
	global_load_lds_dwordx4 v[142:143], off
	v_lshl_add_u64 v[142:143], s[38:39], 0, v[128:129]
	s_mov_b32 m0, s45
	s_nop 0
	global_load_lds_dwordx4 v[142:143], off
	s_barrier
	s_waitcnt lgkmcnt(0)
	s_setprio 1
	s_waitcnt lgkmcnt(0)
	v_mfma_f32_16x16x32_bf16 v[112:115], v[204:207], v[160:163], v[112:115]
	v_mfma_f32_16x16x32_bf16 v[104:107], v[212:215], v[160:163], v[104:107]
	v_mfma_f32_16x16x32_bf16 v[96:99], v[204:207], v[168:171], v[96:99]
	v_mfma_f32_16x16x32_bf16 v[88:91], v[212:215], v[168:171], v[88:91]
	v_mfma_f32_16x16x32_bf16 v[80:83], v[204:207], v[188:191], v[80:83]
	v_mfma_f32_16x16x32_bf16 v[72:75], v[212:215], v[188:191], v[72:75]
	v_mfma_f32_16x16x32_bf16 v[68:71], v[204:207], v[196:199], v[68:71]
	v_mfma_f32_16x16x32_bf16 v[64:67], v[212:215], v[196:199], v[64:67]
	v_mfma_f32_16x16x32_bf16 v[112:115], v[208:211], v[164:167], v[112:115]
	v_mfma_f32_16x16x32_bf16 v[104:107], v[216:219], v[164:167], v[104:107]
	v_mfma_f32_16x16x32_bf16 v[96:99], v[208:211], v[172:175], v[96:99]
	v_mfma_f32_16x16x32_bf16 v[88:91], v[216:219], v[172:175], v[88:91]
	v_mfma_f32_16x16x32_bf16 v[80:83], v[208:211], v[192:195], v[80:83]
	v_mfma_f32_16x16x32_bf16 v[72:75], v[216:219], v[192:195], v[72:75]
	v_mfma_f32_16x16x32_bf16 v[68:71], v[208:211], v[200:203], v[68:71]
	v_mfma_f32_16x16x32_bf16 v[64:67], v[216:219], v[200:203], v[64:67]
	s_setprio 0
	s_mov_b32 m0, s41
	v_lshl_add_u64 v[142:143], s[36:37], 0, v[132:133]
	s_barrier
	ds_read_b128 v[160:163], v139 offset:16384
	ds_read_b128 v[164:167], v139 offset:17408
	ds_read_b128 v[168:171], v139 offset:18432
	ds_read_b128 v[172:175], v139 offset:19456
	ds_read_b128 v[188:191], v139 offset:20480
	ds_read_b128 v[192:195], v139 offset:21504
	ds_read_b128 v[196:199], v139 offset:22528
	ds_read_b128 v[200:203], v139 offset:23552
	global_load_lds_dwordx4 v[142:143], off
	v_lshl_add_u64 v[142:143], s[36:37], 0, v[130:131]
	s_mov_b32 m0, s59
	s_nop 0
	global_load_lds_dwordx4 v[142:143], off
	s_barrier
	s_waitcnt lgkmcnt(0)
	s_setprio 1
	s_waitcnt lgkmcnt(0)
	v_mfma_f32_16x16x32_bf16 v[60:63], v[134:137], v[160:163], v[60:63]
	v_mfma_f32_16x16x32_bf16 v[56:59], v[152:155], v[160:163], v[56:59]
	v_mfma_f32_16x16x32_bf16 v[52:55], v[134:137], v[168:171], v[52:55]
	v_mfma_f32_16x16x32_bf16 v[44:47], v[152:155], v[168:171], v[44:47]
	v_mfma_f32_16x16x32_bf16 v[36:39], v[134:137], v[188:191], v[36:39]
	v_mfma_f32_16x16x32_bf16 v[28:31], v[152:155], v[188:191], v[28:31]
	v_mfma_f32_16x16x32_bf16 v[20:23], v[134:137], v[196:199], v[20:23]
	v_mfma_f32_16x16x32_bf16 v[12:15], v[152:155], v[196:199], v[12:15]
	v_mfma_f32_16x16x32_bf16 v[60:63], v[148:151], v[164:167], v[60:63]
	v_mfma_f32_16x16x32_bf16 v[56:59], v[156:159], v[164:167], v[56:59]
	v_mfma_f32_16x16x32_bf16 v[52:55], v[148:151], v[172:175], v[52:55]
	v_mfma_f32_16x16x32_bf16 v[44:47], v[156:159], v[172:175], v[44:47]
	v_mfma_f32_16x16x32_bf16 v[36:39], v[148:151], v[192:195], v[36:39]
	v_mfma_f32_16x16x32_bf16 v[28:31], v[156:159], v[192:195], v[28:31]
	v_mfma_f32_16x16x32_bf16 v[20:23], v[148:151], v[200:203], v[20:23]
	v_mfma_f32_16x16x32_bf16 v[12:15], v[156:159], v[200:203], v[12:15]
	s_setprio 0
	s_barrier
	s_add_u32 s38, s38, 0x84000
	s_addc_u32 s39, s39, 0
	s_mov_b32 m0, s60
	v_lshl_add_u64 v[134:135], s[38:39], 0, v[144:145]
	global_load_lds_dwordx4 v[134:135], off
	v_lshl_add_u64 v[134:135], s[38:39], 0, v[128:129]
	s_mov_b32 m0, s61
	s_nop 0
	global_load_lds_dwordx4 v[134:135], off
	s_waitcnt vmcnt(6)
	s_barrier
	s_setprio 1
	v_mfma_f32_16x16x32_bf16 v[48:51], v[204:207], v[160:163], v[48:51]
	v_mfma_f32_16x16x32_bf16 v[40:43], v[212:215], v[160:163], v[40:43]
	v_mfma_f32_16x16x32_bf16 v[32:35], v[204:207], v[168:171], v[32:35]
	v_mfma_f32_16x16x32_bf16 v[24:27], v[212:215], v[168:171], v[24:27]
	v_mfma_f32_16x16x32_bf16 v[16:19], v[204:207], v[188:191], v[16:19]
	v_mfma_f32_16x16x32_bf16 v[8:11], v[212:215], v[188:191], v[8:11]
	v_mfma_f32_16x16x32_bf16 v[4:7], v[204:207], v[196:199], v[4:7]
	v_mfma_f32_16x16x32_bf16 v[0:3], v[212:215], v[196:199], v[0:3]
	v_mfma_f32_16x16x32_bf16 v[48:51], v[208:211], v[164:167], v[48:51]
	v_mfma_f32_16x16x32_bf16 v[40:43], v[216:219], v[164:167], v[40:43]
	v_mfma_f32_16x16x32_bf16 v[32:35], v[208:211], v[172:175], v[32:35]
	v_mfma_f32_16x16x32_bf16 v[24:27], v[216:219], v[172:175], v[24:27]
	v_mfma_f32_16x16x32_bf16 v[16:19], v[208:211], v[192:195], v[16:19]
	v_mfma_f32_16x16x32_bf16 v[8:11], v[216:219], v[192:195], v[8:11]
	v_mfma_f32_16x16x32_bf16 v[4:7], v[208:211], v[200:203], v[4:7]
	v_mfma_f32_16x16x32_bf16 v[0:3], v[216:219], v[200:203], v[0:3]
	s_setprio 0
	v_or_b32_e32 v134, 0x18000, v140
	v_add_u32_e32 v142, 0x18400, v140
	s_barrier
	ds_read_b128 v[134:137], v134
	ds_read_b128 v[148:151], v142
	v_add_u32_e32 v142, 0x18800, v140
	v_add_u32_e32 v143, 0x18c00, v140
	ds_read_b128 v[152:155], v142
	ds_read_b128 v[156:159], v143
	s_add_u32 s36, s36, 0x84000
	s_addc_u32 s37, s37, 0
	s_mov_b32 m0, s62
	v_lshl_add_u64 v[142:143], s[36:37], 0, v[132:133]
	ds_read_b128 v[160:163], v139 offset:32768
	ds_read_b128 v[164:167], v139 offset:33792
	ds_read_b128 v[168:171], v139 offset:34816
	ds_read_b128 v[172:175], v139 offset:35840
	ds_read_b128 v[188:191], v139 offset:36864
	ds_read_b128 v[192:195], v139 offset:37888
	ds_read_b128 v[196:199], v139 offset:38912
	ds_read_b128 v[200:203], v139 offset:39936
	global_load_lds_dwordx4 v[142:143], off
	v_lshl_add_u64 v[142:143], s[36:37], 0, v[130:131]
	s_mov_b32 m0, s63
	s_nop 0
	global_load_lds_dwordx4 v[142:143], off
	s_waitcnt lgkmcnt(8)
	s_barrier
	s_waitcnt lgkmcnt(0)
	s_setprio 1
	s_waitcnt lgkmcnt(0)
	v_mfma_f32_16x16x32_bf16 v[124:127], v[134:137], v[160:163], v[124:127]
	v_mfma_f32_16x16x32_bf16 v[120:123], v[152:155], v[160:163], v[120:123]
	v_mfma_f32_16x16x32_bf16 v[116:119], v[134:137], v[168:171], v[116:119]
	v_mfma_f32_16x16x32_bf16 v[108:111], v[152:155], v[168:171], v[108:111]
	v_mfma_f32_16x16x32_bf16 v[100:103], v[134:137], v[188:191], v[100:103]
	v_mfma_f32_16x16x32_bf16 v[92:95], v[152:155], v[188:191], v[92:95]
	v_mfma_f32_16x16x32_bf16 v[84:87], v[134:137], v[196:199], v[84:87]
	v_mfma_f32_16x16x32_bf16 v[76:79], v[152:155], v[196:199], v[76:79]
	v_mfma_f32_16x16x32_bf16 v[124:127], v[148:151], v[164:167], v[124:127]
	v_mfma_f32_16x16x32_bf16 v[120:123], v[156:159], v[164:167], v[120:123]
	v_mfma_f32_16x16x32_bf16 v[116:119], v[148:151], v[172:175], v[116:119]
	v_mfma_f32_16x16x32_bf16 v[108:111], v[156:159], v[172:175], v[108:111]
	v_mfma_f32_16x16x32_bf16 v[100:103], v[148:151], v[192:195], v[100:103]
	v_mfma_f32_16x16x32_bf16 v[92:95], v[156:159], v[192:195], v[92:95]
	v_mfma_f32_16x16x32_bf16 v[84:87], v[148:151], v[200:203], v[84:87]
	v_mfma_f32_16x16x32_bf16 v[76:79], v[156:159], v[200:203], v[76:79]
	s_setprio 0
	s_barrier
	v_or_b32_e32 v142, 0x1c000, v140
	v_add_u32_e32 v143, 0x1c400, v140
	s_add_u32 s36, s89, s90
	ds_read_b128 v[204:207], v142
	ds_read_b128 v[208:211], v143
	v_add_u32_e32 v142, 0x1c800, v140
	v_add_u32_e32 v143, 0x1cc00, v140
	s_addc_u32 s37, s88, 0
	s_mov_b32 m0, s74
	ds_read_b128 v[212:215], v142
	ds_read_b128 v[216:219], v143
	v_lshl_add_u64 v[142:143], s[36:37], 0, v[144:145]
	global_load_lds_dwordx4 v[142:143], off
	v_lshl_add_u64 v[142:143], s[36:37], 0, v[128:129]
	s_mov_b32 m0, s75
	s_nop 0
	global_load_lds_dwordx4 v[142:143], off
	s_barrier
	s_waitcnt lgkmcnt(0)
	s_setprio 1
	s_waitcnt lgkmcnt(0)
	v_mfma_f32_16x16x32_bf16 v[112:115], v[204:207], v[160:163], v[112:115]
	v_mfma_f32_16x16x32_bf16 v[104:107], v[212:215], v[160:163], v[104:107]
	v_mfma_f32_16x16x32_bf16 v[96:99], v[204:207], v[168:171], v[96:99]
	v_mfma_f32_16x16x32_bf16 v[88:91], v[212:215], v[168:171], v[88:91]
	v_mfma_f32_16x16x32_bf16 v[80:83], v[204:207], v[188:191], v[80:83]
	v_mfma_f32_16x16x32_bf16 v[72:75], v[212:215], v[188:191], v[72:75]
	v_mfma_f32_16x16x32_bf16 v[68:71], v[204:207], v[196:199], v[68:71]
	v_mfma_f32_16x16x32_bf16 v[64:67], v[212:215], v[196:199], v[64:67]
	v_mfma_f32_16x16x32_bf16 v[112:115], v[208:211], v[164:167], v[112:115]
	v_mfma_f32_16x16x32_bf16 v[104:107], v[216:219], v[164:167], v[104:107]
	v_mfma_f32_16x16x32_bf16 v[96:99], v[208:211], v[172:175], v[96:99]
	v_mfma_f32_16x16x32_bf16 v[88:91], v[216:219], v[172:175], v[88:91]
	v_mfma_f32_16x16x32_bf16 v[80:83], v[208:211], v[192:195], v[80:83]
	v_mfma_f32_16x16x32_bf16 v[72:75], v[216:219], v[192:195], v[72:75]
	v_mfma_f32_16x16x32_bf16 v[68:71], v[208:211], v[200:203], v[68:71]
	v_mfma_f32_16x16x32_bf16 v[64:67], v[216:219], v[200:203], v[64:67]
	s_setprio 0
	s_mov_b32 m0, s76
	v_lshl_add_u64 v[142:143], s[14:15], 0, v[132:133]
	s_barrier
	ds_read_b128 v[160:163], v139 offset:49152
	ds_read_b128 v[164:167], v139 offset:50176
	ds_read_b128 v[168:171], v139 offset:51200
	ds_read_b128 v[172:175], v139 offset:52224
	ds_read_b128 v[188:191], v139 offset:53248
	ds_read_b128 v[192:195], v139 offset:54272
	ds_read_b128 v[196:199], v139 offset:55296
	ds_read_b128 v[200:203], v139 offset:56320
	global_load_lds_dwordx4 v[142:143], off
	v_lshl_add_u64 v[142:143], s[14:15], 0, v[130:131]
	s_mov_b32 m0, s77
	s_nop 0
	global_load_lds_dwordx4 v[142:143], off
	s_barrier
	s_waitcnt lgkmcnt(0)
	s_setprio 1
	s_waitcnt lgkmcnt(0)
	v_mfma_f32_16x16x32_bf16 v[60:63], v[134:137], v[160:163], v[60:63]
	v_mfma_f32_16x16x32_bf16 v[56:59], v[152:155], v[160:163], v[56:59]
	v_mfma_f32_16x16x32_bf16 v[52:55], v[134:137], v[168:171], v[52:55]
	v_mfma_f32_16x16x32_bf16 v[44:47], v[152:155], v[168:171], v[44:47]
	v_mfma_f32_16x16x32_bf16 v[36:39], v[134:137], v[188:191], v[36:39]
	v_mfma_f32_16x16x32_bf16 v[28:31], v[152:155], v[188:191], v[28:31]
	v_mfma_f32_16x16x32_bf16 v[20:23], v[134:137], v[196:199], v[20:23]
	v_mfma_f32_16x16x32_bf16 v[12:15], v[152:155], v[196:199], v[12:15]
	v_mfma_f32_16x16x32_bf16 v[60:63], v[148:151], v[164:167], v[60:63]
	v_mfma_f32_16x16x32_bf16 v[56:59], v[156:159], v[164:167], v[56:59]
	v_mfma_f32_16x16x32_bf16 v[52:55], v[148:151], v[172:175], v[52:55]
	v_mfma_f32_16x16x32_bf16 v[44:47], v[156:159], v[172:175], v[44:47]
	v_mfma_f32_16x16x32_bf16 v[36:39], v[148:151], v[192:195], v[36:39]
	v_mfma_f32_16x16x32_bf16 v[28:31], v[156:159], v[192:195], v[28:31]
	v_mfma_f32_16x16x32_bf16 v[20:23], v[148:151], v[200:203], v[20:23]
	v_mfma_f32_16x16x32_bf16 v[12:15], v[156:159], v[200:203], v[12:15]
	s_setprio 0
	s_barrier
	s_add_u32 s14, s36, 0x84000
	s_addc_u32 s15, s37, 0
	s_mov_b32 m0, s78
	v_lshl_add_u64 v[134:135], s[14:15], 0, v[144:145]
	global_load_lds_dwordx4 v[134:135], off
	v_lshl_add_u64 v[134:135], s[14:15], 0, v[128:129]
	s_mov_b32 m0, s79
	s_nop 0
	global_load_lds_dwordx4 v[134:135], off
	s_waitcnt vmcnt(6)
	s_barrier
	s_setprio 1
	v_mfma_f32_16x16x32_bf16 v[48:51], v[204:207], v[160:163], v[48:51]
	v_mfma_f32_16x16x32_bf16 v[40:43], v[212:215], v[160:163], v[40:43]
	v_mfma_f32_16x16x32_bf16 v[32:35], v[204:207], v[168:171], v[32:35]
	v_mfma_f32_16x16x32_bf16 v[24:27], v[212:215], v[168:171], v[24:27]
	v_mfma_f32_16x16x32_bf16 v[16:19], v[204:207], v[188:191], v[16:19]
	v_mfma_f32_16x16x32_bf16 v[8:11], v[212:215], v[188:191], v[8:11]
	v_mfma_f32_16x16x32_bf16 v[4:7], v[204:207], v[196:199], v[4:7]
	v_mfma_f32_16x16x32_bf16 v[0:3], v[212:215], v[196:199], v[0:3]
	v_mfma_f32_16x16x32_bf16 v[48:51], v[208:211], v[164:167], v[48:51]
	v_mfma_f32_16x16x32_bf16 v[40:43], v[216:219], v[164:167], v[40:43]
	v_mfma_f32_16x16x32_bf16 v[32:35], v[208:211], v[172:175], v[32:35]
	v_mfma_f32_16x16x32_bf16 v[24:27], v[216:219], v[172:175], v[24:27]
	v_mfma_f32_16x16x32_bf16 v[16:19], v[208:211], v[192:195], v[16:19]
	v_mfma_f32_16x16x32_bf16 v[8:11], v[216:219], v[192:195], v[8:11]
	v_mfma_f32_16x16x32_bf16 v[4:7], v[208:211], v[200:203], v[4:7]
	v_mfma_f32_16x16x32_bf16 v[0:3], v[216:219], v[200:203], v[0:3]
	s_setprio 0
	s_addk_i32 s85, 0x100
	s_cmp_gt_u32 s86, 29
	s_mov_b32 s86, s87
	s_barrier
	s_cbranch_scc0 .LBB0_494
	v_readlane_b32 s10, v252, 58
	v_lshl_add_u32 v146, s84, 8, v138
	v_lshl_or_b32 v136, s83, 8, v141
	v_readlane_b32 s11, v252, 59
	v_ashrrev_i32_e32 v137, 31, v136
	v_cvt_pk_bf16_f32 v68, v68, v69
	v_cvt_pk_bf16_f32 v69, v70, v71
	v_cvt_pk_bf16_f32 v70, v64, v65
	v_add_u32_e32 v64, 0x80, v146
	v_mov_b64_e32 v[134:135], s[10:11]
	v_mad_i64_i32 v[142:143], s[10:11], v146, s70, v[134:135]
	v_lshlrev_b64 v[136:137], 1, v[136:137]
	v_cvt_pk_bf16_f32 v112, v112, v113
	v_cvt_pk_bf16_f32 v113, v114, v115
	v_cvt_pk_bf16_f32 v114, v104, v105
	v_or_b32_e32 v104, 16, v146
	v_mad_i64_i32 v[64:65], s[10:11], v64, s70, v[134:135]
	v_cvt_pk_bf16_f32 v48, v48, v49
	v_cvt_pk_bf16_f32 v49, v50, v51
	v_cvt_pk_bf16_f32 v50, v40, v41
	v_add_u32_e32 v40, 0x90, v146
	v_lshl_add_u64 v[142:143], v[142:143], 0, v[136:137]
	v_mad_i64_i32 v[104:105], s[10:11], v104, s70, v[134:135]
	v_cvt_pk_bf16_f32 v96, v96, v97
	v_cvt_pk_bf16_f32 v97, v98, v99
	v_cvt_pk_bf16_f32 v98, v88, v89
	v_or_b32_e32 v88, 32, v146
	v_lshl_add_u64 v[64:65], v[64:65], 0, v[136:137]
	v_mad_i64_i32 v[40:41], s[10:11], v40, s70, v[134:135]
	v_cvt_pk_bf16_f32 v32, v32, v33
	v_cvt_pk_bf16_f32 v33, v34, v35
	v_cvt_pk_bf16_f32 v34, v24, v25
	v_add_u32_e32 v24, 0xa0, v146
	v_cvt_pk_bf16_f32 v115, v106, v107
	global_store_dwordx4 v[142:143], v[112:115], off offset:256
	v_mad_i64_i32 v[88:89], s[10:11], v88, s70, v[134:135]
	s_nop 0
	v_lshl_add_u64 v[112:113], v[104:105], 0, v[136:137]
	v_cvt_pk_bf16_f32 v80, v80, v81
	v_cvt_pk_bf16_f32 v81, v82, v83
	v_cvt_pk_bf16_f32 v82, v72, v73
	v_or_b32_e32 v72, 48, v146
	v_cvt_pk_bf16_f32 v51, v42, v43
	global_store_dwordx4 v[64:65], v[48:51], off offset:256
	v_mad_i64_i32 v[24:25], s[10:11], v24, s70, v[134:135]
	s_nop 0
	v_lshl_add_u64 v[48:49], v[40:41], 0, v[136:137]
	v_cvt_pk_bf16_f32 v16, v16, v17
	v_cvt_pk_bf16_f32 v17, v18, v19
	v_cvt_pk_bf16_f32 v18, v8, v9
	v_add_u32_e32 v8, 0xb0, v146
	v_cvt_pk_bf16_f32 v99, v90, v91
	global_store_dwordx4 v[112:113], v[96:99], off offset:256
	v_mad_i64_i32 v[72:73], s[10:11], v72, s70, v[134:135]
	s_nop 0
	v_lshl_add_u64 v[96:97], v[88:89], 0, v[136:137]
	v_cvt_pk_bf16_f32 v35, v26, v27
	global_store_dwordx4 v[48:49], v[32:35], off offset:256
	v_mad_i64_i32 v[8:9], s[10:11], v8, s70, v[134:135]
	s_nop 0
	v_lshl_add_u64 v[32:33], v[24:25], 0, v[136:137]
	v_cvt_pk_bf16_f32 v83, v74, v75
	global_store_dwordx4 v[96:97], v[80:83], off offset:256
	v_cvt_pk_bf16_f32 v19, v10, v11
	global_store_dwordx4 v[32:33], v[16:19], off offset:256
	s_and_b64 vcc, exec, s[0:1]
	v_lshl_add_u64 v[80:81], v[72:73], 0, v[136:137]
	v_lshl_add_u64 v[16:17], v[8:9], 0, v[136:137]
	s_mov_b32 s83, s81
	s_mov_b32 s84, s82
	s_mov_b64 s[10:11], s[6:7]
	s_mov_b64 s[12:13], s[4:5]
	v_cvt_pk_bf16_f32 v124, v124, v125
	v_cvt_pk_bf16_f32 v125, v126, v127
	v_cvt_pk_bf16_f32 v126, v120, v121
	v_cvt_pk_bf16_f32 v127, v122, v123
	global_store_dwordx4 v[142:143], v[124:127], off
	v_cvt_pk_bf16_f32 v104, v116, v117
	v_cvt_pk_bf16_f32 v105, v118, v119
	v_cvt_pk_bf16_f32 v106, v108, v109
	v_cvt_pk_bf16_f32 v107, v110, v111
	global_store_dwordx4 v[112:113], v[104:107], off
	v_cvt_pk_bf16_f32 v88, v100, v101
	v_cvt_pk_bf16_f32 v89, v102, v103
	v_cvt_pk_bf16_f32 v90, v92, v93
	v_cvt_pk_bf16_f32 v91, v94, v95
	global_store_dwordx4 v[96:97], v[88:91], off
	v_cvt_pk_bf16_f32 v72, v84, v85
	v_cvt_pk_bf16_f32 v73, v86, v87
	v_cvt_pk_bf16_f32 v74, v76, v77
	v_cvt_pk_bf16_f32 v75, v78, v79
	global_store_dwordx4 v[80:81], v[72:75], off
	v_cvt_pk_bf16_f32 v71, v66, v67
	global_store_dwordx4 v[80:81], v[68:71], off offset:256
	v_cvt_pk_bf16_f32 v60, v60, v61
	v_cvt_pk_bf16_f32 v61, v62, v63
	v_cvt_pk_bf16_f32 v62, v56, v57
	v_cvt_pk_bf16_f32 v63, v58, v59
	global_store_dwordx4 v[64:65], v[60:63], off
	v_cvt_pk_bf16_f32 v40, v52, v53
	v_cvt_pk_bf16_f32 v41, v54, v55
	v_cvt_pk_bf16_f32 v42, v44, v45
	v_cvt_pk_bf16_f32 v43, v46, v47
	global_store_dwordx4 v[48:49], v[40:43], off
	v_cvt_pk_bf16_f32 v24, v36, v37
	v_cvt_pk_bf16_f32 v25, v38, v39
	v_cvt_pk_bf16_f32 v26, v28, v29
	v_cvt_pk_bf16_f32 v27, v30, v31
	global_store_dwordx4 v[32:33], v[24:27], off
	v_cvt_pk_bf16_f32 v8, v20, v21
	v_cvt_pk_bf16_f32 v9, v22, v23
	v_cvt_pk_bf16_f32 v10, v12, v13
	v_cvt_pk_bf16_f32 v11, v14, v15
	global_store_dwordx4 v[16:17], v[8:11], off
	v_cvt_pk_bf16_f32 v4, v4, v5
	v_cvt_pk_bf16_f32 v5, v6, v7
	v_cvt_pk_bf16_f32 v6, v0, v1
	v_cvt_pk_bf16_f32 v7, v2, v3
	global_store_dwordx4 v[16:17], v[4:7], off offset:256
	s_cbranch_vccz .LBB0_483
	s_waitcnt vmcnt(0)
	s_cmpk_gt_u32 s34, 0xff
	s_cbranch_scc1 .LBB0_498
	s_barrier
